# widened H stores of the fused residual epilogue non-temporal
# speedup vs baseline: 1.0066x; 1.0066x over previous
; __device__ __forceinline__ unsigned cvt_pk_bf16(float lo, float hi) { unsigned r; asm volatile("v_cvt_pk_bf16_f32 %0, %1, %2" : "=v"(r) : "v"(lo), "v"(hi)); return r; }
;     __device__ __forceinline__ void fused(f32x4 (&acc)[2][2][4][2], const Unit& u, int wr, int wc, int fr, int fq, ldsp lds, int wid, int lane) const {
;     ...
;         const int colt = u.pn * BM + wc * 32 + 4 * fq;
;         const float* mb = modn + (size_t)b * NMOD;
; #pragma unroll
;         for (int bj = 0; bj < 2; ++bj)
; #pragma unroll
;             for (int n = 0; n < 2; ++n) { const int c = colt + bj * HALF + n * 16;
;                 f32x4 gc = *(const f32x4*)(gain + c), sh = (f32x4){0.f, 0.f, 0.f, 0.f};
;                 if (!fin) { gc = gc * (*(const f32x4*)(mb + scoff + c) + 1.0f); sh = *(const f32x4*)(mb + shoff + c); }
; #pragma unroll
;                 for (int ai = 0; ai < 2; ++ai)
; #pragma unroll
;                     for (int m = 0; m < 4; ++m) { const int r = ai * HALF + wr * 64 + m * 16 + fr; const float rs = Sx[r];
;                         const f32x4 y = (acc[ai][bj][m][n] * rs) * gc + sh;
;                         if (fin) *(f32x4*)(xd + (size_t)(rowt + r) * D + c) = y;
;                         else { u32x2 w; w.x = cvt_pk_bf16(y[0], y[1]); w.y = cvt_pk_bf16(y[2], y[3]); *(u32x2*)(H + (size_t)(rowt + r) * D + c) = w; } } }
.LBB0_487:
	ds_read_b32 v108, v96 offset:4096
	s_mov_b64 s[6:7], -1
	s_and_b64 vcc, exec, s[84:85]
	s_waitcnt lgkmcnt(0)
	v_pk_mul_f32 v[94:95], v[94:95], v[108:109] op_sel_hi:[1,0]
	v_pk_mul_f32 v[92:93], v[92:93], v[108:109] op_sel_hi:[1,0]
	v_pk_fma_f32 v[94:95], v[100:101], v[94:95], v[104:105]
	v_pk_fma_f32 v[92:93], v[98:99], v[92:93], v[102:103]
	s_cbranch_vccz .LBB0_489
	v_add_u32_e32 v110, s8, v148
	v_ashrrev_i32_e32 v111, 31, v110
	v_readlane_b32 s4, v254, 35
	v_lshlrev_b64 v[110:111], 11, v[110:111]
	v_readlane_b32 s5, v254, 36
	v_cvt_pk_bf16_f32 v108, v92, v93
	v_cvt_pk_bf16_f32 v109, v94, v95
	s_mov_b64 s[6:7], 0
	s_nop 0
	v_lshl_add_u64 v[110:111], s[4:5], 0, v[110:111]
	v_lshl_add_u64 v[110:111], v[142:143], 1, v[110:111]
	v_mov_b64_e32 v[240:241], v[108:109]
	v_bfe_u32 v194, v196, 4, 1
	v_mov_b32_e32 v195, 0
	v_mul_u32_u24_e32 v194, 24, v194
	v_lshl_add_u64 v[110:111], v[110:111], 0, v[194:195]
	v_permlane16_swap_b32_e32 v238, v240
	v_permlane16_swap_b32_e32 v239, v241
	global_store_dwordx4 v[110:111], v[238:241], off nt

; __device__ __forceinline__ unsigned cvt_pk_bf16(float lo, float hi) { unsigned r; asm volatile("v_cvt_pk_bf16_f32 %0, %1, %2" : "=v"(r) : "v"(lo), "v"(hi)); return r; }
;     __device__ __forceinline__ void fused(f32x4 (&acc)[2][2][4][2], const Unit& u, int wr, int wc, int fr, int fq, ldsp lds, int wid, int lane) const {
;     ...
;         const int colt = u.pn * BM + wc * 32 + 4 * fq;
;         const float* mb = modn + (size_t)b * NMOD;
; #pragma unroll
;         for (int bj = 0; bj < 2; ++bj)
; #pragma unroll
;             for (int n = 0; n < 2; ++n) { const int c = colt + bj * HALF + n * 16;
;                 f32x4 gc = *(const f32x4*)(gain + c), sh = (f32x4){0.f, 0.f, 0.f, 0.f};
;                 if (!fin) { gc = gc * (*(const f32x4*)(mb + scoff + c) + 1.0f); sh = *(const f32x4*)(mb + shoff + c); }
; #pragma unroll
;                 for (int ai = 0; ai < 2; ++ai)
; #pragma unroll
;                     for (int m = 0; m < 4; ++m) { const int r = ai * HALF + wr * 64 + m * 16 + fr; const float rs = Sx[r];
;                         const f32x4 y = (acc[ai][bj][m][n] * rs) * gc + sh;
;                         if (fin) *(f32x4*)(xd + (size_t)(rowt + r) * D + c) = y;
;                         else { u32x2 w; w.x = cvt_pk_bf16(y[0], y[1]); w.y = cvt_pk_bf16(y[2], y[3]); *(u32x2*)(H + (size_t)(rowt + r) * D + c) = w; } } }
.LBB0_491:
	ds_read_b32 v92, v96 offset:4160
	s_mov_b64 s[6:7], -1
	s_and_b64 vcc, exec, s[84:85]
	s_waitcnt lgkmcnt(0)
	v_pk_mul_f32 v[90:91], v[90:91], v[92:93] op_sel_hi:[1,0]
	v_pk_mul_f32 v[88:89], v[88:89], v[92:93] op_sel_hi:[1,0]
	v_pk_fma_f32 v[90:91], v[100:101], v[90:91], v[104:105]
	v_pk_fma_f32 v[88:89], v[98:99], v[88:89], v[102:103]
	s_cbranch_vccz .LBB0_493
	v_add_u32_e32 v94, s8, v138
	v_ashrrev_i32_e32 v95, 31, v94
	v_readlane_b32 s4, v254, 35
	v_lshlrev_b64 v[94:95], 11, v[94:95]
	v_readlane_b32 s5, v254, 36
	v_cvt_pk_bf16_f32 v92, v88, v89
	v_cvt_pk_bf16_f32 v93, v90, v91
	s_mov_b64 s[6:7], 0
	s_nop 0
	v_lshl_add_u64 v[94:95], s[4:5], 0, v[94:95]
	v_lshl_add_u64 v[94:95], v[142:143], 1, v[94:95]
	v_mov_b64_e32 v[244:245], v[92:93]
	v_bfe_u32 v194, v196, 4, 1
	v_mov_b32_e32 v195, 0
	v_mul_u32_u24_e32 v194, 24, v194
	v_lshl_add_u64 v[94:95], v[94:95], 0, v[194:195]
	v_permlane16_swap_b32_e32 v242, v244
	v_permlane16_swap_b32_e32 v243, v245
	global_store_dwordx4 v[94:95], v[242:245], off nt

; __device__ __forceinline__ unsigned cvt_pk_bf16(float lo, float hi) { unsigned r; asm volatile("v_cvt_pk_bf16_f32 %0, %1, %2" : "=v"(r) : "v"(lo), "v"(hi)); return r; }
;     __device__ __forceinline__ void fused(f32x4 (&acc)[2][2][4][2], const Unit& u, int wr, int wc, int fr, int fq, ldsp lds, int wid, int lane) const {
;     ...
;         const int colt = u.pn * BM + wc * 32 + 4 * fq;
;         const float* mb = modn + (size_t)b * NMOD;
; #pragma unroll
;         for (int bj = 0; bj < 2; ++bj)
; #pragma unroll
;             for (int n = 0; n < 2; ++n) { const int c = colt + bj * HALF + n * 16;
;                 f32x4 gc = *(const f32x4*)(gain + c), sh = (f32x4){0.f, 0.f, 0.f, 0.f};
;                 if (!fin) { gc = gc * (*(const f32x4*)(mb + scoff + c) + 1.0f); sh = *(const f32x4*)(mb + shoff + c); }
; #pragma unroll
;                 for (int ai = 0; ai < 2; ++ai)
; #pragma unroll
;                     for (int m = 0; m < 4; ++m) { const int r = ai * HALF + wr * 64 + m * 16 + fr; const float rs = Sx[r];
;                         const f32x4 y = (acc[ai][bj][m][n] * rs) * gc + sh;
;                         if (fin) *(f32x4*)(xd + (size_t)(rowt + r) * D + c) = y;
;                         else { u32x2 w; w.x = cvt_pk_bf16(y[0], y[1]); w.y = cvt_pk_bf16(y[2], y[3]); *(u32x2*)(H + (size_t)(rowt + r) * D + c) = w; } } }
.LBB0_495:
	ds_read_b32 v88, v96 offset:4224
	s_mov_b64 s[6:7], -1
	s_and_b64 vcc, exec, s[84:85]
	s_waitcnt lgkmcnt(0)
	v_pk_mul_f32 v[86:87], v[86:87], v[88:89] op_sel_hi:[1,0]
	v_pk_mul_f32 v[84:85], v[84:85], v[88:89] op_sel_hi:[1,0]
	v_pk_fma_f32 v[86:87], v[100:101], v[86:87], v[104:105]
	v_pk_fma_f32 v[84:85], v[98:99], v[84:85], v[102:103]
	s_cbranch_vccz .LBB0_497
	v_add_u32_e32 v90, s8, v134
	v_ashrrev_i32_e32 v91, 31, v90
	v_readlane_b32 s4, v254, 35
	v_lshlrev_b64 v[90:91], 11, v[90:91]
	v_readlane_b32 s5, v254, 36
	v_cvt_pk_bf16_f32 v88, v84, v85
	v_cvt_pk_bf16_f32 v89, v86, v87
	s_mov_b64 s[6:7], 0
	s_nop 0
	v_lshl_add_u64 v[90:91], s[4:5], 0, v[90:91]
	v_lshl_add_u64 v[90:91], v[142:143], 1, v[90:91]
	v_mov_b64_e32 v[248:249], v[88:89]
	v_bfe_u32 v194, v196, 4, 1
	v_mov_b32_e32 v195, 0
	v_mul_u32_u24_e32 v194, 24, v194
	v_lshl_add_u64 v[90:91], v[90:91], 0, v[194:195]
	v_permlane16_swap_b32_e32 v246, v248
	v_permlane16_swap_b32_e32 v247, v249
	global_store_dwordx4 v[90:91], v[246:249], off nt

; __device__ __forceinline__ unsigned cvt_pk_bf16(float lo, float hi) { unsigned r; asm volatile("v_cvt_pk_bf16_f32 %0, %1, %2" : "=v"(r) : "v"(lo), "v"(hi)); return r; }
;     __device__ __forceinline__ void fused(f32x4 (&acc)[2][2][4][2], const Unit& u, int wr, int wc, int fr, int fq, ldsp lds, int wid, int lane) const {
;     ...
;         const int colt = u.pn * BM + wc * 32 + 4 * fq;
;         const float* mb = modn + (size_t)b * NMOD;
; #pragma unroll
;         for (int bj = 0; bj < 2; ++bj)
; #pragma unroll
;             for (int n = 0; n < 2; ++n) { const int c = colt + bj * HALF + n * 16;
;                 f32x4 gc = *(const f32x4*)(gain + c), sh = (f32x4){0.f, 0.f, 0.f, 0.f};
;                 if (!fin) { gc = gc * (*(const f32x4*)(mb + scoff + c) + 1.0f); sh = *(const f32x4*)(mb + shoff + c); }
; #pragma unroll
;                 for (int ai = 0; ai < 2; ++ai)
; #pragma unroll
;                     for (int m = 0; m < 4; ++m) { const int r = ai * HALF + wr * 64 + m * 16 + fr; const float rs = Sx[r];
;                         const f32x4 y = (acc[ai][bj][m][n] * rs) * gc + sh;
;                         if (fin) *(f32x4*)(xd + (size_t)(rowt + r) * D + c) = y;
;                         else { u32x2 w; w.x = cvt_pk_bf16(y[0], y[1]); w.y = cvt_pk_bf16(y[2], y[3]); *(u32x2*)(H + (size_t)(rowt + r) * D + c) = w; } } }
.LBB0_499:
	ds_read_b32 v84, v96 offset:4288
	s_mov_b64 s[6:7], -1
	s_and_b64 vcc, exec, s[84:85]
	s_waitcnt lgkmcnt(0)
	v_pk_mul_f32 v[82:83], v[82:83], v[84:85] op_sel_hi:[1,0]
	v_pk_mul_f32 v[80:81], v[80:81], v[84:85] op_sel_hi:[1,0]
	v_pk_fma_f32 v[82:83], v[100:101], v[82:83], v[104:105]
	v_pk_fma_f32 v[80:81], v[98:99], v[80:81], v[102:103]
	s_cbranch_vccz .LBB0_501
	v_add_u32_e32 v86, s8, v130
	v_ashrrev_i32_e32 v87, 31, v86
	v_readlane_b32 s4, v254, 35
	v_lshlrev_b64 v[86:87], 11, v[86:87]
	v_readlane_b32 s5, v254, 36
	v_cvt_pk_bf16_f32 v84, v80, v81
	v_cvt_pk_bf16_f32 v85, v82, v83
	s_mov_b64 s[6:7], 0
	s_nop 0
	v_lshl_add_u64 v[86:87], s[4:5], 0, v[86:87]
	v_lshl_add_u64 v[86:87], v[142:143], 1, v[86:87]
	v_mov_b64_e32 v[252:253], v[84:85]
	v_bfe_u32 v194, v196, 4, 1
	v_mov_b32_e32 v195, 0
	v_mul_u32_u24_e32 v194, 24, v194
	v_lshl_add_u64 v[86:87], v[86:87], 0, v[194:195]
	v_permlane16_swap_b32_e32 v250, v252
	v_permlane16_swap_b32_e32 v251, v253
	global_store_dwordx4 v[86:87], v[250:253], off nt

; __device__ __forceinline__ unsigned cvt_pk_bf16(float lo, float hi) { unsigned r; asm volatile("v_cvt_pk_bf16_f32 %0, %1, %2" : "=v"(r) : "v"(lo), "v"(hi)); return r; }
;     __device__ __forceinline__ void fused(f32x4 (&acc)[2][2][4][2], const Unit& u, int wr, int wc, int fr, int fq, ldsp lds, int wid, int lane) const {
;     ...
;         const int colt = u.pn * BM + wc * 32 + 4 * fq;
;         const float* mb = modn + (size_t)b * NMOD;
; #pragma unroll
;         for (int bj = 0; bj < 2; ++bj)
; #pragma unroll
;             for (int n = 0; n < 2; ++n) { const int c = colt + bj * HALF + n * 16;
;                 f32x4 gc = *(const f32x4*)(gain + c), sh = (f32x4){0.f, 0.f, 0.f, 0.f};
;                 if (!fin) { gc = gc * (*(const f32x4*)(mb + scoff + c) + 1.0f); sh = *(const f32x4*)(mb + shoff + c); }
; #pragma unroll
;                 for (int ai = 0; ai < 2; ++ai)
; #pragma unroll
;                     for (int m = 0; m < 4; ++m) { const int r = ai * HALF + wr * 64 + m * 16 + fr; const float rs = Sx[r];
;                         const f32x4 y = (acc[ai][bj][m][n] * rs) * gc + sh;
;                         if (fin) *(f32x4*)(xd + (size_t)(rowt + r) * D + c) = y;
;                         else { u32x2 w; w.x = cvt_pk_bf16(y[0], y[1]); w.y = cvt_pk_bf16(y[2], y[3]); *(u32x2*)(H + (size_t)(rowt + r) * D + c) = w; } } }
.LBB0_503:
	ds_read_b32 v80, v96 offset:4608
	s_mov_b64 s[6:7], -1
	s_and_b64 vcc, exec, s[84:85]
	s_waitcnt lgkmcnt(0)
	v_pk_mul_f32 v[78:79], v[78:79], v[80:81] op_sel_hi:[1,0]
	v_pk_mul_f32 v[76:77], v[76:77], v[80:81] op_sel_hi:[1,0]
	v_pk_fma_f32 v[78:79], v[100:101], v[78:79], v[104:105]
	v_pk_fma_f32 v[76:77], v[98:99], v[76:77], v[102:103]
	s_cbranch_vccz .LBB0_505
	v_add_u32_e32 v82, s8, v126
	v_ashrrev_i32_e32 v83, 31, v82
	v_readlane_b32 s4, v254, 35
	v_lshlrev_b64 v[82:83], 11, v[82:83]
	v_readlane_b32 s5, v254, 36
	v_cvt_pk_bf16_f32 v80, v76, v77
	v_cvt_pk_bf16_f32 v81, v78, v79
	s_mov_b64 s[6:7], 0
	s_nop 0
	v_lshl_add_u64 v[82:83], s[4:5], 0, v[82:83]
	v_lshl_add_u64 v[82:83], v[142:143], 1, v[82:83]
	v_mov_b64_e32 v[204:205], v[80:81]
	v_bfe_u32 v194, v196, 4, 1
	v_mov_b32_e32 v195, 0
	v_mul_u32_u24_e32 v194, 24, v194
	v_lshl_add_u64 v[82:83], v[82:83], 0, v[194:195]
	v_permlane16_swap_b32_e32 v202, v204
	v_permlane16_swap_b32_e32 v203, v205
	global_store_dwordx4 v[82:83], v[202:205], off nt

; __device__ __forceinline__ unsigned cvt_pk_bf16(float lo, float hi) { unsigned r; asm volatile("v_cvt_pk_bf16_f32 %0, %1, %2" : "=v"(r) : "v"(lo), "v"(hi)); return r; }
;     __device__ __forceinline__ void fused(f32x4 (&acc)[2][2][4][2], const Unit& u, int wr, int wc, int fr, int fq, ldsp lds, int wid, int lane) const {
;     ...
;         const int colt = u.pn * BM + wc * 32 + 4 * fq;
;         const float* mb = modn + (size_t)b * NMOD;
; #pragma unroll
;         for (int bj = 0; bj < 2; ++bj)
; #pragma unroll
;             for (int n = 0; n < 2; ++n) { const int c = colt + bj * HALF + n * 16;
;                 f32x4 gc = *(const f32x4*)(gain + c), sh = (f32x4){0.f, 0.f, 0.f, 0.f};
;                 if (!fin) { gc = gc * (*(const f32x4*)(mb + scoff + c) + 1.0f); sh = *(const f32x4*)(mb + shoff + c); }
; #pragma unroll
;                 for (int ai = 0; ai < 2; ++ai)
; #pragma unroll
;                     for (int m = 0; m < 4; ++m) { const int r = ai * HALF + wr * 64 + m * 16 + fr; const float rs = Sx[r];
;                         const f32x4 y = (acc[ai][bj][m][n] * rs) * gc + sh;
;                         if (fin) *(f32x4*)(xd + (size_t)(rowt + r) * D + c) = y;
;                         else { u32x2 w; w.x = cvt_pk_bf16(y[0], y[1]); w.y = cvt_pk_bf16(y[2], y[3]); *(u32x2*)(H + (size_t)(rowt + r) * D + c) = w; } } }
.LBB0_507:
	ds_read_b32 v76, v96 offset:4672
	s_mov_b64 s[6:7], -1
	s_and_b64 vcc, exec, s[84:85]
	s_waitcnt lgkmcnt(0)
	v_pk_mul_f32 v[74:75], v[74:75], v[76:77] op_sel_hi:[1,0]
	v_pk_mul_f32 v[72:73], v[72:73], v[76:77] op_sel_hi:[1,0]
	v_pk_fma_f32 v[74:75], v[100:101], v[74:75], v[104:105]
	v_pk_fma_f32 v[72:73], v[98:99], v[72:73], v[102:103]
	s_cbranch_vccz .LBB0_509
	v_add_u32_e32 v78, s8, v118
	v_ashrrev_i32_e32 v79, 31, v78
	v_readlane_b32 s4, v254, 35
	v_lshlrev_b64 v[78:79], 11, v[78:79]
	v_readlane_b32 s5, v254, 36
	v_cvt_pk_bf16_f32 v76, v72, v73
	v_cvt_pk_bf16_f32 v77, v74, v75
	s_mov_b64 s[6:7], 0
	s_nop 0
	v_lshl_add_u64 v[78:79], s[4:5], 0, v[78:79]
	v_lshl_add_u64 v[78:79], v[142:143], 1, v[78:79]
	v_mov_b64_e32 v[208:209], v[76:77]
	v_bfe_u32 v194, v196, 4, 1
	v_mov_b32_e32 v195, 0
	v_mul_u32_u24_e32 v194, 24, v194
	v_lshl_add_u64 v[78:79], v[78:79], 0, v[194:195]
	v_permlane16_swap_b32_e32 v206, v208
	v_permlane16_swap_b32_e32 v207, v209
	global_store_dwordx4 v[78:79], v[206:209], off nt

; __device__ __forceinline__ unsigned cvt_pk_bf16(float lo, float hi) { unsigned r; asm volatile("v_cvt_pk_bf16_f32 %0, %1, %2" : "=v"(r) : "v"(lo), "v"(hi)); return r; }
;     __device__ __forceinline__ void fused(f32x4 (&acc)[2][2][4][2], const Unit& u, int wr, int wc, int fr, int fq, ldsp lds, int wid, int lane) const {
;     ...
;         const int colt = u.pn * BM + wc * 32 + 4 * fq;
;         const float* mb = modn + (size_t)b * NMOD;
; #pragma unroll
;         for (int bj = 0; bj < 2; ++bj)
; #pragma unroll
;             for (int n = 0; n < 2; ++n) { const int c = colt + bj * HALF + n * 16;
;                 f32x4 gc = *(const f32x4*)(gain + c), sh = (f32x4){0.f, 0.f, 0.f, 0.f};
;                 if (!fin) { gc = gc * (*(const f32x4*)(mb + scoff + c) + 1.0f); sh = *(const f32x4*)(mb + shoff + c); }
; #pragma unroll
;                 for (int ai = 0; ai < 2; ++ai)
; #pragma unroll
;                     for (int m = 0; m < 4; ++m) { const int r = ai * HALF + wr * 64 + m * 16 + fr; const float rs = Sx[r];
;                         const f32x4 y = (acc[ai][bj][m][n] * rs) * gc + sh;
;                         if (fin) *(f32x4*)(xd + (size_t)(rowt + r) * D + c) = y;
;                         else { u32x2 w; w.x = cvt_pk_bf16(y[0], y[1]); w.y = cvt_pk_bf16(y[2], y[3]); *(u32x2*)(H + (size_t)(rowt + r) * D + c) = w; } } }
.LBB0_511:
	ds_read_b32 v72, v96 offset:4736
	s_mov_b64 s[6:7], -1
	s_and_b64 vcc, exec, s[84:85]
	s_waitcnt lgkmcnt(0)
	v_pk_mul_f32 v[70:71], v[70:71], v[72:73] op_sel_hi:[1,0]
	v_pk_mul_f32 v[68:69], v[68:69], v[72:73] op_sel_hi:[1,0]
	v_pk_fma_f32 v[70:71], v[100:101], v[70:71], v[104:105]
	v_pk_fma_f32 v[68:69], v[98:99], v[68:69], v[102:103]
	s_cbranch_vccz .LBB0_513
	v_add_u32_e32 v74, s8, v114
	v_ashrrev_i32_e32 v75, 31, v74
	v_readlane_b32 s4, v254, 35
	v_lshlrev_b64 v[74:75], 11, v[74:75]
	v_readlane_b32 s5, v254, 36
	v_cvt_pk_bf16_f32 v72, v68, v69
	v_cvt_pk_bf16_f32 v73, v70, v71
	s_mov_b64 s[6:7], 0
	s_nop 0
	v_lshl_add_u64 v[74:75], s[4:5], 0, v[74:75]
	v_lshl_add_u64 v[74:75], v[142:143], 1, v[74:75]
	v_mov_b64_e32 v[212:213], v[72:73]
	v_bfe_u32 v194, v196, 4, 1
	v_mov_b32_e32 v195, 0
	v_mul_u32_u24_e32 v194, 24, v194
	v_lshl_add_u64 v[74:75], v[74:75], 0, v[194:195]
	v_permlane16_swap_b32_e32 v210, v212
	v_permlane16_swap_b32_e32 v211, v213
	global_store_dwordx4 v[74:75], v[210:213], off nt

; __device__ __forceinline__ unsigned cvt_pk_bf16(float lo, float hi) { unsigned r; asm volatile("v_cvt_pk_bf16_f32 %0, %1, %2" : "=v"(r) : "v"(lo), "v"(hi)); return r; }
;     __device__ __forceinline__ void fused(f32x4 (&acc)[2][2][4][2], const Unit& u, int wr, int wc, int fr, int fq, ldsp lds, int wid, int lane) const {
;     ...
;         const int colt = u.pn * BM + wc * 32 + 4 * fq;
;         const float* mb = modn + (size_t)b * NMOD;
; #pragma unroll
;         for (int bj = 0; bj < 2; ++bj)
; #pragma unroll
;             for (int n = 0; n < 2; ++n) { const int c = colt + bj * HALF + n * 16;
;                 f32x4 gc = *(const f32x4*)(gain + c), sh = (f32x4){0.f, 0.f, 0.f, 0.f};
;                 if (!fin) { gc = gc * (*(const f32x4*)(mb + scoff + c) + 1.0f); sh = *(const f32x4*)(mb + shoff + c); }
; #pragma unroll
;                 for (int ai = 0; ai < 2; ++ai)
; #pragma unroll
;                     for (int m = 0; m < 4; ++m) { const int r = ai * HALF + wr * 64 + m * 16 + fr; const float rs = Sx[r];
;                         const f32x4 y = (acc[ai][bj][m][n] * rs) * gc + sh;
;                         if (fin) *(f32x4*)(xd + (size_t)(rowt + r) * D + c) = y;
;                         else { u32x2 w; w.x = cvt_pk_bf16(y[0], y[1]); w.y = cvt_pk_bf16(y[2], y[3]); *(u32x2*)(H + (size_t)(rowt + r) * D + c) = w; } } }
.LBB0_515:
	ds_read_b32 v68, v96 offset:4800
	s_mov_b64 s[6:7], -1
	s_and_b64 vcc, exec, s[84:85]
	s_waitcnt lgkmcnt(0)
	v_pk_mul_f32 v[66:67], v[66:67], v[68:69] op_sel_hi:[1,0]
	v_pk_mul_f32 v[64:65], v[64:65], v[68:69] op_sel_hi:[1,0]
	v_pk_fma_f32 v[66:67], v[100:101], v[66:67], v[104:105]
	v_pk_fma_f32 v[64:65], v[98:99], v[64:65], v[102:103]
	s_cbranch_vccz .LBB0_519
	v_add_u32_e32 v70, s8, v106
	v_ashrrev_i32_e32 v71, 31, v70
	v_readlane_b32 s4, v254, 35
	v_lshlrev_b64 v[70:71], 11, v[70:71]
	v_readlane_b32 s5, v254, 36
	v_cvt_pk_bf16_f32 v68, v64, v65
	v_cvt_pk_bf16_f32 v69, v66, v67
	s_nop 1
	v_lshl_add_u64 v[70:71], s[4:5], 0, v[70:71]
	v_lshl_add_u64 v[70:71], v[142:143], 1, v[70:71]
	v_mov_b64_e32 v[192:193], v[68:69]
	v_bfe_u32 v194, v196, 4, 1
	v_mov_b32_e32 v195, 0
	v_mul_u32_u24_e32 v194, 24, v194
	v_lshl_add_u64 v[70:71], v[70:71], 0, v[194:195]
	v_permlane16_swap_b32_e32 v190, v192
	v_permlane16_swap_b32_e32 v191, v193
	global_store_dwordx4 v[70:71], v[190:193], off nt
	s_cbranch_execz .LBB0_520

; __device__ __forceinline__ unsigned cvt_pk_bf16(float lo, float hi) { unsigned r; asm volatile("v_cvt_pk_bf16_f32 %0, %1, %2" : "=v"(r) : "v"(lo), "v"(hi)); return r; }
;     __device__ __forceinline__ void fused(f32x4 (&acc)[2][2][4][2], const Unit& u, int wr, int wc, int fr, int fq, ldsp lds, int wid, int lane) const {
;     ...
;         const int colt = u.pn * BM + wc * 32 + 4 * fq;
;         const float* mb = modn + (size_t)b * NMOD;
; #pragma unroll
;         for (int bj = 0; bj < 2; ++bj)
; #pragma unroll
;             for (int n = 0; n < 2; ++n) { const int c = colt + bj * HALF + n * 16;
;                 f32x4 gc = *(const f32x4*)(gain + c), sh = (f32x4){0.f, 0.f, 0.f, 0.f};
;                 if (!fin) { gc = gc * (*(const f32x4*)(mb + scoff + c) + 1.0f); sh = *(const f32x4*)(mb + shoff + c); }
; #pragma unroll
;                 for (int ai = 0; ai < 2; ++ai)
; #pragma unroll
;                     for (int m = 0; m < 4; ++m) { const int r = ai * HALF + wr * 64 + m * 16 + fr; const float rs = Sx[r];
;                         const f32x4 y = (acc[ai][bj][m][n] * rs) * gc + sh;
;                         if (fin) *(f32x4*)(xd + (size_t)(rowt + r) * D + c) = y;
;                         else { u32x2 w; w.x = cvt_pk_bf16(y[0], y[1]); w.y = cvt_pk_bf16(y[2], y[3]); *(u32x2*)(H + (size_t)(rowt + r) * D + c) = w; } } }
.LBB0_557:
	ds_read_b32 v40, v96 offset:4096
	s_mov_b64 s[6:7], -1
	s_and_b64 vcc, exec, s[84:85]
	s_waitcnt lgkmcnt(0)
	v_pk_mul_f32 v[30:31], v[30:31], v[40:41] op_sel_hi:[1,0]
	v_pk_mul_f32 v[28:29], v[28:29], v[40:41] op_sel_hi:[1,0]
	v_pk_fma_f32 v[30:31], v[34:35], v[30:31], v[38:39]
	v_pk_fma_f32 v[28:29], v[32:33], v[28:29], v[36:37]
	s_cbranch_vccz .LBB0_559
	v_add_u32_e32 v42, s8, v148
	v_ashrrev_i32_e32 v43, 31, v42
	v_readlane_b32 s0, v254, 35
	v_lshlrev_b64 v[42:43], 11, v[42:43]
	v_readlane_b32 s1, v254, 36
	v_cvt_pk_bf16_f32 v40, v28, v29
	v_cvt_pk_bf16_f32 v41, v30, v31
	s_mov_b64 s[6:7], 0
	s_nop 0
	v_lshl_add_u64 v[42:43], s[0:1], 0, v[42:43]
	v_lshl_add_u64 v[42:43], v[142:143], 1, v[42:43]
	v_mov_b64_e32 v[240:241], v[40:41]
	v_bfe_u32 v194, v196, 4, 1
	v_mov_b32_e32 v195, 0
	v_mul_u32_u24_e32 v194, 24, v194
	v_lshl_add_u64 v[42:43], v[42:43], 0, v[194:195]
	v_permlane16_swap_b32_e32 v238, v240
	v_permlane16_swap_b32_e32 v239, v241
	global_store_dwordx4 v[42:43], v[238:241], off offset:256 nt

; __device__ __forceinline__ unsigned cvt_pk_bf16(float lo, float hi) { unsigned r; asm volatile("v_cvt_pk_bf16_f32 %0, %1, %2" : "=v"(r) : "v"(lo), "v"(hi)); return r; }
;     __device__ __forceinline__ void fused(f32x4 (&acc)[2][2][4][2], const Unit& u, int wr, int wc, int fr, int fq, ldsp lds, int wid, int lane) const {
;     ...
;         const int colt = u.pn * BM + wc * 32 + 4 * fq;
;         const float* mb = modn + (size_t)b * NMOD;
; #pragma unroll
;         for (int bj = 0; bj < 2; ++bj)
; #pragma unroll
;             for (int n = 0; n < 2; ++n) { const int c = colt + bj * HALF + n * 16;
;                 f32x4 gc = *(const f32x4*)(gain + c), sh = (f32x4){0.f, 0.f, 0.f, 0.f};
;                 if (!fin) { gc = gc * (*(const f32x4*)(mb + scoff + c) + 1.0f); sh = *(const f32x4*)(mb + shoff + c); }
; #pragma unroll
;                 for (int ai = 0; ai < 2; ++ai)
; #pragma unroll
;                     for (int m = 0; m < 4; ++m) { const int r = ai * HALF + wr * 64 + m * 16 + fr; const float rs = Sx[r];
;                         const f32x4 y = (acc[ai][bj][m][n] * rs) * gc + sh;
;                         if (fin) *(f32x4*)(xd + (size_t)(rowt + r) * D + c) = y;
;                         else { u32x2 w; w.x = cvt_pk_bf16(y[0], y[1]); w.y = cvt_pk_bf16(y[2], y[3]); *(u32x2*)(H + (size_t)(rowt + r) * D + c) = w; } } }
.LBB0_561:
	ds_read_b32 v28, v96 offset:4160
	s_mov_b64 s[6:7], -1
	s_and_b64 vcc, exec, s[84:85]
	s_waitcnt lgkmcnt(0)
	v_pk_mul_f32 v[26:27], v[26:27], v[28:29] op_sel_hi:[1,0]
	v_pk_mul_f32 v[24:25], v[24:25], v[28:29] op_sel_hi:[1,0]
	v_pk_fma_f32 v[26:27], v[34:35], v[26:27], v[38:39]
	v_pk_fma_f32 v[24:25], v[32:33], v[24:25], v[36:37]
	s_cbranch_vccz .LBB0_563
	v_add_u32_e32 v30, s8, v138
	v_ashrrev_i32_e32 v31, 31, v30
	v_readlane_b32 s0, v254, 35
	v_lshlrev_b64 v[30:31], 11, v[30:31]
	v_readlane_b32 s1, v254, 36
	v_cvt_pk_bf16_f32 v28, v24, v25
	v_cvt_pk_bf16_f32 v29, v26, v27
	s_mov_b64 s[6:7], 0
	s_nop 0
	v_lshl_add_u64 v[30:31], s[0:1], 0, v[30:31]
	v_lshl_add_u64 v[30:31], v[142:143], 1, v[30:31]
	v_mov_b64_e32 v[244:245], v[28:29]
	v_bfe_u32 v194, v196, 4, 1
	v_mov_b32_e32 v195, 0
	v_mul_u32_u24_e32 v194, 24, v194
	v_lshl_add_u64 v[30:31], v[30:31], 0, v[194:195]
	v_permlane16_swap_b32_e32 v242, v244
	v_permlane16_swap_b32_e32 v243, v245
	global_store_dwordx4 v[30:31], v[242:245], off offset:256 nt

; __device__ __forceinline__ unsigned cvt_pk_bf16(float lo, float hi) { unsigned r; asm volatile("v_cvt_pk_bf16_f32 %0, %1, %2" : "=v"(r) : "v"(lo), "v"(hi)); return r; }
;     __device__ __forceinline__ void fused(f32x4 (&acc)[2][2][4][2], const Unit& u, int wr, int wc, int fr, int fq, ldsp lds, int wid, int lane) const {
;     ...
;         const int colt = u.pn * BM + wc * 32 + 4 * fq;
;         const float* mb = modn + (size_t)b * NMOD;
; #pragma unroll
;         for (int bj = 0; bj < 2; ++bj)
; #pragma unroll
;             for (int n = 0; n < 2; ++n) { const int c = colt + bj * HALF + n * 16;
;                 f32x4 gc = *(const f32x4*)(gain + c), sh = (f32x4){0.f, 0.f, 0.f, 0.f};
;                 if (!fin) { gc = gc * (*(const f32x4*)(mb + scoff + c) + 1.0f); sh = *(const f32x4*)(mb + shoff + c); }
; #pragma unroll
;                 for (int ai = 0; ai < 2; ++ai)
; #pragma unroll
;                     for (int m = 0; m < 4; ++m) { const int r = ai * HALF + wr * 64 + m * 16 + fr; const float rs = Sx[r];
;                         const f32x4 y = (acc[ai][bj][m][n] * rs) * gc + sh;
;                         if (fin) *(f32x4*)(xd + (size_t)(rowt + r) * D + c) = y;
;                         else { u32x2 w; w.x = cvt_pk_bf16(y[0], y[1]); w.y = cvt_pk_bf16(y[2], y[3]); *(u32x2*)(H + (size_t)(rowt + r) * D + c) = w; } } }
.LBB0_565:
	ds_read_b32 v24, v96 offset:4224
	s_mov_b64 s[6:7], -1
	s_and_b64 vcc, exec, s[84:85]
	s_waitcnt lgkmcnt(0)
	v_pk_mul_f32 v[22:23], v[22:23], v[24:25] op_sel_hi:[1,0]
	v_pk_mul_f32 v[20:21], v[20:21], v[24:25] op_sel_hi:[1,0]
	v_pk_fma_f32 v[22:23], v[34:35], v[22:23], v[38:39]
	v_pk_fma_f32 v[20:21], v[32:33], v[20:21], v[36:37]
	s_cbranch_vccz .LBB0_567
	v_add_u32_e32 v26, s8, v134
	v_ashrrev_i32_e32 v27, 31, v26
	v_readlane_b32 s0, v254, 35
	v_lshlrev_b64 v[26:27], 11, v[26:27]
	v_readlane_b32 s1, v254, 36
	v_cvt_pk_bf16_f32 v24, v20, v21
	v_cvt_pk_bf16_f32 v25, v22, v23
	s_mov_b64 s[6:7], 0
	s_nop 0
	v_lshl_add_u64 v[26:27], s[0:1], 0, v[26:27]
	v_lshl_add_u64 v[26:27], v[142:143], 1, v[26:27]
	v_mov_b64_e32 v[248:249], v[24:25]
	v_bfe_u32 v194, v196, 4, 1
	v_mov_b32_e32 v195, 0
	v_mul_u32_u24_e32 v194, 24, v194
	v_lshl_add_u64 v[26:27], v[26:27], 0, v[194:195]
	v_permlane16_swap_b32_e32 v246, v248
	v_permlane16_swap_b32_e32 v247, v249
	global_store_dwordx4 v[26:27], v[246:249], off offset:256 nt

; __device__ __forceinline__ unsigned cvt_pk_bf16(float lo, float hi) { unsigned r; asm volatile("v_cvt_pk_bf16_f32 %0, %1, %2" : "=v"(r) : "v"(lo), "v"(hi)); return r; }
;     __device__ __forceinline__ void fused(f32x4 (&acc)[2][2][4][2], const Unit& u, int wr, int wc, int fr, int fq, ldsp lds, int wid, int lane) const {
;     ...
;         const int colt = u.pn * BM + wc * 32 + 4 * fq;
;         const float* mb = modn + (size_t)b * NMOD;
; #pragma unroll
;         for (int bj = 0; bj < 2; ++bj)
; #pragma unroll
;             for (int n = 0; n < 2; ++n) { const int c = colt + bj * HALF + n * 16;
;                 f32x4 gc = *(const f32x4*)(gain + c), sh = (f32x4){0.f, 0.f, 0.f, 0.f};
;                 if (!fin) { gc = gc * (*(const f32x4*)(mb + scoff + c) + 1.0f); sh = *(const f32x4*)(mb + shoff + c); }
; #pragma unroll
;                 for (int ai = 0; ai < 2; ++ai)
; #pragma unroll
;                     for (int m = 0; m < 4; ++m) { const int r = ai * HALF + wr * 64 + m * 16 + fr; const float rs = Sx[r];
;                         const f32x4 y = (acc[ai][bj][m][n] * rs) * gc + sh;
;                         if (fin) *(f32x4*)(xd + (size_t)(rowt + r) * D + c) = y;
;                         else { u32x2 w; w.x = cvt_pk_bf16(y[0], y[1]); w.y = cvt_pk_bf16(y[2], y[3]); *(u32x2*)(H + (size_t)(rowt + r) * D + c) = w; } } }
.LBB0_569:
	ds_read_b32 v20, v96 offset:4288
	s_mov_b64 s[6:7], -1
	s_and_b64 vcc, exec, s[84:85]
	s_waitcnt lgkmcnt(0)
	v_pk_mul_f32 v[18:19], v[18:19], v[20:21] op_sel_hi:[1,0]
	v_pk_mul_f32 v[16:17], v[16:17], v[20:21] op_sel_hi:[1,0]
	v_pk_fma_f32 v[18:19], v[34:35], v[18:19], v[38:39]
	v_pk_fma_f32 v[16:17], v[32:33], v[16:17], v[36:37]
	s_cbranch_vccz .LBB0_571
	v_add_u32_e32 v22, s8, v130
	v_ashrrev_i32_e32 v23, 31, v22
	v_readlane_b32 s0, v254, 35
	v_lshlrev_b64 v[22:23], 11, v[22:23]
	v_readlane_b32 s1, v254, 36
	v_cvt_pk_bf16_f32 v20, v16, v17
	v_cvt_pk_bf16_f32 v21, v18, v19
	s_mov_b64 s[6:7], 0
	s_nop 0
	v_lshl_add_u64 v[22:23], s[0:1], 0, v[22:23]
	v_lshl_add_u64 v[22:23], v[142:143], 1, v[22:23]
	v_mov_b64_e32 v[252:253], v[20:21]
	v_bfe_u32 v194, v196, 4, 1
	v_mov_b32_e32 v195, 0
	v_mul_u32_u24_e32 v194, 24, v194
	v_lshl_add_u64 v[22:23], v[22:23], 0, v[194:195]
	v_permlane16_swap_b32_e32 v250, v252
	v_permlane16_swap_b32_e32 v251, v253
	global_store_dwordx4 v[22:23], v[250:253], off offset:256 nt

; __device__ __forceinline__ unsigned cvt_pk_bf16(float lo, float hi) { unsigned r; asm volatile("v_cvt_pk_bf16_f32 %0, %1, %2" : "=v"(r) : "v"(lo), "v"(hi)); return r; }
;     __device__ __forceinline__ void fused(f32x4 (&acc)[2][2][4][2], const Unit& u, int wr, int wc, int fr, int fq, ldsp lds, int wid, int lane) const {
;     ...
;         const int colt = u.pn * BM + wc * 32 + 4 * fq;
;         const float* mb = modn + (size_t)b * NMOD;
; #pragma unroll
;         for (int bj = 0; bj < 2; ++bj)
; #pragma unroll
;             for (int n = 0; n < 2; ++n) { const int c = colt + bj * HALF + n * 16;
;                 f32x4 gc = *(const f32x4*)(gain + c), sh = (f32x4){0.f, 0.f, 0.f, 0.f};
;                 if (!fin) { gc = gc * (*(const f32x4*)(mb + scoff + c) + 1.0f); sh = *(const f32x4*)(mb + shoff + c); }
; #pragma unroll
;                 for (int ai = 0; ai < 2; ++ai)
; #pragma unroll
;                     for (int m = 0; m < 4; ++m) { const int r = ai * HALF + wr * 64 + m * 16 + fr; const float rs = Sx[r];
;                         const f32x4 y = (acc[ai][bj][m][n] * rs) * gc + sh;
;                         if (fin) *(f32x4*)(xd + (size_t)(rowt + r) * D + c) = y;
;                         else { u32x2 w; w.x = cvt_pk_bf16(y[0], y[1]); w.y = cvt_pk_bf16(y[2], y[3]); *(u32x2*)(H + (size_t)(rowt + r) * D + c) = w; } } }
.LBB0_573:
	ds_read_b32 v16, v96 offset:4608
	s_mov_b64 s[6:7], -1
	s_and_b64 vcc, exec, s[84:85]
	s_waitcnt lgkmcnt(0)
	v_pk_mul_f32 v[14:15], v[14:15], v[16:17] op_sel_hi:[1,0]
	v_pk_mul_f32 v[12:13], v[12:13], v[16:17] op_sel_hi:[1,0]
	v_pk_fma_f32 v[14:15], v[34:35], v[14:15], v[38:39]
	v_pk_fma_f32 v[12:13], v[32:33], v[12:13], v[36:37]
	s_cbranch_vccz .LBB0_575
	v_add_u32_e32 v18, s8, v126
	v_ashrrev_i32_e32 v19, 31, v18
	v_readlane_b32 s0, v254, 35
	v_lshlrev_b64 v[18:19], 11, v[18:19]
	v_readlane_b32 s1, v254, 36
	v_cvt_pk_bf16_f32 v16, v12, v13
	v_cvt_pk_bf16_f32 v17, v14, v15
	s_mov_b64 s[6:7], 0
	s_nop 0
	v_lshl_add_u64 v[18:19], s[0:1], 0, v[18:19]
	v_lshl_add_u64 v[18:19], v[142:143], 1, v[18:19]
	v_mov_b64_e32 v[204:205], v[16:17]
	v_bfe_u32 v194, v196, 4, 1
	v_mov_b32_e32 v195, 0
	v_mul_u32_u24_e32 v194, 24, v194
	v_lshl_add_u64 v[18:19], v[18:19], 0, v[194:195]
	v_permlane16_swap_b32_e32 v202, v204
	v_permlane16_swap_b32_e32 v203, v205
	global_store_dwordx4 v[18:19], v[202:205], off offset:256 nt

; __device__ __forceinline__ unsigned cvt_pk_bf16(float lo, float hi) { unsigned r; asm volatile("v_cvt_pk_bf16_f32 %0, %1, %2" : "=v"(r) : "v"(lo), "v"(hi)); return r; }
;     __device__ __forceinline__ void fused(f32x4 (&acc)[2][2][4][2], const Unit& u, int wr, int wc, int fr, int fq, ldsp lds, int wid, int lane) const {
;     ...
;         const int colt = u.pn * BM + wc * 32 + 4 * fq;
;         const float* mb = modn + (size_t)b * NMOD;
; #pragma unroll
;         for (int bj = 0; bj < 2; ++bj)
; #pragma unroll
;             for (int n = 0; n < 2; ++n) { const int c = colt + bj * HALF + n * 16;
;                 f32x4 gc = *(const f32x4*)(gain + c), sh = (f32x4){0.f, 0.f, 0.f, 0.f};
;                 if (!fin) { gc = gc * (*(const f32x4*)(mb + scoff + c) + 1.0f); sh = *(const f32x4*)(mb + shoff + c); }
; #pragma unroll
;                 for (int ai = 0; ai < 2; ++ai)
; #pragma unroll
;                     for (int m = 0; m < 4; ++m) { const int r = ai * HALF + wr * 64 + m * 16 + fr; const float rs = Sx[r];
;                         const f32x4 y = (acc[ai][bj][m][n] * rs) * gc + sh;
;                         if (fin) *(f32x4*)(xd + (size_t)(rowt + r) * D + c) = y;
;                         else { u32x2 w; w.x = cvt_pk_bf16(y[0], y[1]); w.y = cvt_pk_bf16(y[2], y[3]); *(u32x2*)(H + (size_t)(rowt + r) * D + c) = w; } } }
.LBB0_577:
	ds_read_b32 v12, v96 offset:4672
	s_mov_b64 s[6:7], -1
	s_and_b64 vcc, exec, s[84:85]
	s_waitcnt lgkmcnt(0)
	v_pk_mul_f32 v[10:11], v[10:11], v[12:13] op_sel_hi:[1,0]
	v_pk_mul_f32 v[8:9], v[8:9], v[12:13] op_sel_hi:[1,0]
	v_pk_fma_f32 v[10:11], v[34:35], v[10:11], v[38:39]
	v_pk_fma_f32 v[8:9], v[32:33], v[8:9], v[36:37]
	s_cbranch_vccz .LBB0_579
	v_add_u32_e32 v14, s8, v118
	v_ashrrev_i32_e32 v15, 31, v14
	v_readlane_b32 s0, v254, 35
	v_lshlrev_b64 v[14:15], 11, v[14:15]
	v_readlane_b32 s1, v254, 36
	v_cvt_pk_bf16_f32 v12, v8, v9
	v_cvt_pk_bf16_f32 v13, v10, v11
	s_mov_b64 s[6:7], 0
	s_nop 0
	v_lshl_add_u64 v[14:15], s[0:1], 0, v[14:15]
	v_lshl_add_u64 v[14:15], v[142:143], 1, v[14:15]
	v_mov_b64_e32 v[208:209], v[12:13]
	v_bfe_u32 v194, v196, 4, 1
	v_mov_b32_e32 v195, 0
	v_mul_u32_u24_e32 v194, 24, v194
	v_lshl_add_u64 v[14:15], v[14:15], 0, v[194:195]
	v_permlane16_swap_b32_e32 v206, v208
	v_permlane16_swap_b32_e32 v207, v209
	global_store_dwordx4 v[14:15], v[206:209], off offset:256 nt

; __device__ __forceinline__ unsigned cvt_pk_bf16(float lo, float hi) { unsigned r; asm volatile("v_cvt_pk_bf16_f32 %0, %1, %2" : "=v"(r) : "v"(lo), "v"(hi)); return r; }
;     __device__ __forceinline__ void fused(f32x4 (&acc)[2][2][4][2], const Unit& u, int wr, int wc, int fr, int fq, ldsp lds, int wid, int lane) const {
;     ...
;         const int colt = u.pn * BM + wc * 32 + 4 * fq;
;         const float* mb = modn + (size_t)b * NMOD;
; #pragma unroll
;         for (int bj = 0; bj < 2; ++bj)
; #pragma unroll
;             for (int n = 0; n < 2; ++n) { const int c = colt + bj * HALF + n * 16;
;                 f32x4 gc = *(const f32x4*)(gain + c), sh = (f32x4){0.f, 0.f, 0.f, 0.f};
;                 if (!fin) { gc = gc * (*(const f32x4*)(mb + scoff + c) + 1.0f); sh = *(const f32x4*)(mb + shoff + c); }
; #pragma unroll
;                 for (int ai = 0; ai < 2; ++ai)
; #pragma unroll
;                     for (int m = 0; m < 4; ++m) { const int r = ai * HALF + wr * 64 + m * 16 + fr; const float rs = Sx[r];
;                         const f32x4 y = (acc[ai][bj][m][n] * rs) * gc + sh;
;                         if (fin) *(f32x4*)(xd + (size_t)(rowt + r) * D + c) = y;
;                         else { u32x2 w; w.x = cvt_pk_bf16(y[0], y[1]); w.y = cvt_pk_bf16(y[2], y[3]); *(u32x2*)(H + (size_t)(rowt + r) * D + c) = w; } } }
.LBB0_581:
	ds_read_b32 v8, v96 offset:4736
	s_mov_b64 s[6:7], -1
	s_and_b64 vcc, exec, s[84:85]
	s_waitcnt lgkmcnt(0)
	v_pk_mul_f32 v[6:7], v[6:7], v[8:9] op_sel_hi:[1,0]
	v_pk_mul_f32 v[4:5], v[4:5], v[8:9] op_sel_hi:[1,0]
	v_pk_fma_f32 v[6:7], v[34:35], v[6:7], v[38:39]
	v_pk_fma_f32 v[4:5], v[32:33], v[4:5], v[36:37]
	s_cbranch_vccz .LBB0_583
	v_add_u32_e32 v10, s8, v114
	v_ashrrev_i32_e32 v11, 31, v10
	v_readlane_b32 s0, v254, 35
	v_lshlrev_b64 v[10:11], 11, v[10:11]
	v_readlane_b32 s1, v254, 36
	v_cvt_pk_bf16_f32 v8, v4, v5
	v_cvt_pk_bf16_f32 v9, v6, v7
	s_mov_b64 s[6:7], 0
	s_nop 0
	v_lshl_add_u64 v[10:11], s[0:1], 0, v[10:11]
	v_lshl_add_u64 v[10:11], v[142:143], 1, v[10:11]
	v_mov_b64_e32 v[212:213], v[8:9]
	v_bfe_u32 v194, v196, 4, 1
	v_mov_b32_e32 v195, 0
	v_mul_u32_u24_e32 v194, 24, v194
	v_lshl_add_u64 v[10:11], v[10:11], 0, v[194:195]
	v_permlane16_swap_b32_e32 v210, v212
	v_permlane16_swap_b32_e32 v211, v213
	global_store_dwordx4 v[10:11], v[210:213], off offset:256 nt

; __device__ __forceinline__ unsigned cvt_pk_bf16(float lo, float hi) { unsigned r; asm volatile("v_cvt_pk_bf16_f32 %0, %1, %2" : "=v"(r) : "v"(lo), "v"(hi)); return r; }
;     __device__ __forceinline__ void fused(f32x4 (&acc)[2][2][4][2], const Unit& u, int wr, int wc, int fr, int fq, ldsp lds, int wid, int lane) const {
;     ...
;         const int colt = u.pn * BM + wc * 32 + 4 * fq;
;         const float* mb = modn + (size_t)b * NMOD;
; #pragma unroll
;         for (int bj = 0; bj < 2; ++bj)
; #pragma unroll
;             for (int n = 0; n < 2; ++n) { const int c = colt + bj * HALF + n * 16;
;                 f32x4 gc = *(const f32x4*)(gain + c), sh = (f32x4){0.f, 0.f, 0.f, 0.f};
;                 if (!fin) { gc = gc * (*(const f32x4*)(mb + scoff + c) + 1.0f); sh = *(const f32x4*)(mb + shoff + c); }
; #pragma unroll
;                 for (int ai = 0; ai < 2; ++ai)
; #pragma unroll
;                     for (int m = 0; m < 4; ++m) { const int r = ai * HALF + wr * 64 + m * 16 + fr; const float rs = Sx[r];
;                         const f32x4 y = (acc[ai][bj][m][n] * rs) * gc + sh;
;                         if (fin) *(f32x4*)(xd + (size_t)(rowt + r) * D + c) = y;
;                         else { u32x2 w; w.x = cvt_pk_bf16(y[0], y[1]); w.y = cvt_pk_bf16(y[2], y[3]); *(u32x2*)(H + (size_t)(rowt + r) * D + c) = w; } } }
.LBB0_585:
	ds_read_b32 v4, v96 offset:4800
	s_mov_b64 s[6:7], -1
	s_and_b64 vcc, exec, s[84:85]
	s_waitcnt lgkmcnt(0)
	v_pk_mul_f32 v[2:3], v[2:3], v[4:5] op_sel_hi:[1,0]
	v_pk_mul_f32 v[0:1], v[0:1], v[4:5] op_sel_hi:[1,0]
	v_pk_fma_f32 v[2:3], v[34:35], v[2:3], v[38:39]
	v_pk_fma_f32 v[0:1], v[32:33], v[0:1], v[36:37]
	s_cbranch_vccz .LBB0_587
	v_add_u32_e32 v6, s8, v106
	v_ashrrev_i32_e32 v7, 31, v6
	v_readlane_b32 s0, v254, 35
	v_lshlrev_b64 v[6:7], 11, v[6:7]
	v_readlane_b32 s1, v254, 36
	v_cvt_pk_bf16_f32 v4, v0, v1
	v_cvt_pk_bf16_f32 v5, v2, v3
	s_mov_b64 s[6:7], 0
	s_nop 0
	v_lshl_add_u64 v[6:7], s[0:1], 0, v[6:7]
	v_lshl_add_u64 v[6:7], v[142:143], 1, v[6:7]
	v_mov_b64_e32 v[192:193], v[4:5]
	v_bfe_u32 v194, v196, 4, 1
	v_mov_b32_e32 v195, 0
	v_mul_u32_u24_e32 v194, 24, v194
	v_lshl_add_u64 v[6:7], v[6:7], 0, v[194:195]
	v_permlane16_swap_b32_e32 v190, v192
	v_permlane16_swap_b32_e32 v191, v193
	global_store_dwordx4 v[6:7], v[190:193], off offset:256 nt
